# second LayerNorm instance: all 16 row loads issued together with counted vmcnt (bit-identical sums)
# baseline (speedup 1.0000x reference)
.LBB0_725:
	v_add_co_u32_e32 v136, vcc, s90, v100
	s_nop 1
	v_addc_co_u32_e32 v137, vcc, -1, v101, vcc
	v_add_co_u32_e32 v138, vcc, s89, v100
	s_nop 1
	v_addc_co_u32_e32 v139, vcc, -1, v101, vcc
	v_add_co_u32_e32 v140, vcc, s94, v100
	s_nop 1
	v_addc_co_u32_e32 v141, vcc, -1, v101, vcc
	v_add_co_u32_e32 v142, vcc, 0xffffc3f8, v100
	s_nop 1
	v_addc_co_u32_e32 v143, vcc, -1, v101, vcc
	global_load_dwordx4 v[46:49], v[136:137], off
	global_load_dwordx4 v[42:45], v[136:137], off offset:1024
	global_load_dwordx4 v[38:41], v[136:137], off offset:2048
	global_load_dwordx4 v[34:37], v[136:137], off offset:3072
	global_load_dwordx4 v[62:65], v[138:139], off
	global_load_dwordx4 v[58:61], v[138:139], off offset:1024
	global_load_dwordx4 v[54:57], v[138:139], off offset:2048
	global_load_dwordx4 v[50:53], v[138:139], off offset:3072
	global_load_dwordx4 v[78:81], v[140:141], off
	global_load_dwordx4 v[74:77], v[140:141], off offset:1024
	global_load_dwordx4 v[70:73], v[140:141], off offset:2048
	global_load_dwordx4 v[66:69], v[140:141], off offset:3072
	global_load_dwordx4 v[94:97], v[142:143], off
	global_load_dwordx4 v[90:93], v[142:143], off offset:1024
	global_load_dwordx4 v[86:89], v[142:143], off offset:2048
	global_load_dwordx4 v[82:85], v[142:143], off offset:3072
	s_mov_b32 s10, 0x3727c5ac
	s_mov_b32 s5, 0x800000
	s_waitcnt vmcnt(12)
	v_add_f32_e32 v145, v46, v47
	v_add_f32_e32 v145, v145, v48
	v_add_f32_e32 v145, v145, v49
	v_add_f32_e32 v145, 0, v145
	v_add_f32_e32 v144, v42, v43
	v_add_f32_e32 v144, v144, v44
	v_add_f32_e32 v144, v144, v45
	v_add_f32_e32 v145, v145, v144
	v_add_f32_e32 v144, v38, v39
	v_add_f32_e32 v144, v144, v40
	v_add_f32_e32 v144, v144, v41
	v_add_f32_e32 v145, v145, v144
	v_add_f32_e32 v144, v34, v35
	v_add_f32_e32 v144, v144, v36
	v_add_f32_e32 v144, v144, v37
	v_add_f32_e32 v105, v145, v144
	s_waitcnt vmcnt(8)
	v_add_f32_e32 v145, v62, v63
	v_add_f32_e32 v145, v145, v64
	v_add_f32_e32 v145, v145, v65
	v_add_f32_e32 v145, 0, v145
	v_add_f32_e32 v144, v58, v59
	v_add_f32_e32 v144, v144, v60
	v_add_f32_e32 v144, v144, v61
	v_add_f32_e32 v145, v145, v144
	v_add_f32_e32 v144, v54, v55
	v_add_f32_e32 v144, v144, v56
	v_add_f32_e32 v144, v144, v57
	v_add_f32_e32 v145, v145, v144
	v_add_f32_e32 v144, v50, v51
	v_add_f32_e32 v144, v144, v52
	v_add_f32_e32 v144, v144, v53
	v_add_f32_e32 v104, v145, v144
	s_waitcnt vmcnt(4)
	v_add_f32_e32 v145, v78, v79
	v_add_f32_e32 v145, v145, v80
	v_add_f32_e32 v145, v145, v81
	v_add_f32_e32 v145, 0, v145
	v_add_f32_e32 v144, v74, v75
	v_add_f32_e32 v144, v144, v76
	v_add_f32_e32 v144, v144, v77
	v_add_f32_e32 v145, v145, v144
	v_add_f32_e32 v144, v70, v71
	v_add_f32_e32 v144, v144, v72
	v_add_f32_e32 v144, v144, v73
	v_add_f32_e32 v145, v145, v144
	v_add_f32_e32 v144, v66, v67
	v_add_f32_e32 v144, v144, v68
	v_add_f32_e32 v144, v144, v69
	v_add_f32_e32 v102, v145, v144
	s_waitcnt vmcnt(0)
	v_add_f32_e32 v145, v94, v95
	v_add_f32_e32 v145, v145, v96
	v_add_f32_e32 v145, v145, v97
	v_add_f32_e32 v145, 0, v145
	v_add_f32_e32 v144, v90, v91
	v_add_f32_e32 v144, v144, v92
	v_add_f32_e32 v144, v144, v93
	v_add_f32_e32 v145, v145, v144
	v_add_f32_e32 v144, v86, v87
	v_add_f32_e32 v144, v144, v88
	v_add_f32_e32 v144, v144, v89
	v_add_f32_e32 v145, v145, v144
	v_add_f32_e32 v144, v82, v83
	v_add_f32_e32 v144, v144, v84
	v_add_f32_e32 v144, v144, v85
	v_add_f32_e32 v0, v145, v144
	ds_swizzle_b32 v106, v0 offset:swizzle(SWAP,1)
	s_waitcnt lgkmcnt(0)
	v_add_f32_e32 v0, v0, v106
	ds_swizzle_b32 v106, v0 offset:swizzle(SWAP,2)
	s_waitcnt lgkmcnt(0)
	v_add_f32_e32 v0, v0, v106
	ds_swizzle_b32 v106, v0 offset:swizzle(SWAP,4)
	s_waitcnt lgkmcnt(0)
	v_add_f32_e32 v0, v0, v106
	ds_swizzle_b32 v106, v0 offset:swizzle(SWAP,8)
	s_waitcnt lgkmcnt(0)
	v_add_f32_e32 v0, v0, v106
	ds_swizzle_b32 v106, v0 offset:swizzle(SWAP,16)
	s_waitcnt lgkmcnt(0)
	v_add_f32_e32 v0, v0, v106
	v_mov_b32_e32 v106, v0
	s_nop 1
	v_permlane32_swap_b32_e32 v0, v106
	v_add_f32_e32 v0, v0, v106
	ds_swizzle_b32 v106, v102 offset:swizzle(SWAP,1)
	v_mul_f32_e32 v0, 0x3a800000, v0
	v_pk_add_f32 v[108:109], v[94:95], v[0:1] op_sel_hi:[1,0] neg_lo:[0,1] neg_hi:[0,1]
	v_pk_add_f32 v[94:95], v[92:93], v[0:1] op_sel_hi:[1,0] neg_lo:[0,1] neg_hi:[0,1]
	v_mov_b32_e32 v92, v109
	s_waitcnt lgkmcnt(0)
	v_add_f32_e32 v102, v102, v106
	ds_swizzle_b32 v106, v102 offset:swizzle(SWAP,2)
	s_waitcnt lgkmcnt(0)
	v_add_f32_e32 v102, v102, v106
	ds_swizzle_b32 v106, v102 offset:swizzle(SWAP,4)
	s_waitcnt lgkmcnt(0)
	v_add_f32_e32 v102, v102, v106
	ds_swizzle_b32 v106, v102 offset:swizzle(SWAP,8)
	s_waitcnt lgkmcnt(0)
	v_add_f32_e32 v102, v102, v106
	ds_swizzle_b32 v106, v102 offset:swizzle(SWAP,16)
	s_waitcnt lgkmcnt(0)
	v_add_f32_e32 v102, v102, v106
	v_mov_b32_e32 v106, v102
	s_nop 1
	v_permlane32_swap_b32_e32 v102, v106
	v_add_f32_e32 v102, v102, v106
	ds_swizzle_b32 v106, v104 offset:swizzle(SWAP,1)
	v_mul_f32_e32 v102, 0x3a800000, v102
	s_waitcnt lgkmcnt(0)
	v_add_f32_e32 v104, v104, v106
	ds_swizzle_b32 v106, v104 offset:swizzle(SWAP,2)
	s_waitcnt lgkmcnt(0)
	v_add_f32_e32 v104, v104, v106
	ds_swizzle_b32 v106, v104 offset:swizzle(SWAP,4)
	s_waitcnt lgkmcnt(0)
	v_add_f32_e32 v104, v104, v106
	ds_swizzle_b32 v106, v104 offset:swizzle(SWAP,8)
	s_waitcnt lgkmcnt(0)
	v_add_f32_e32 v104, v104, v106
	ds_swizzle_b32 v106, v104 offset:swizzle(SWAP,16)
	s_waitcnt lgkmcnt(0)
	v_add_f32_e32 v104, v104, v106
	v_mov_b32_e32 v106, v104
	s_nop 1
	v_permlane32_swap_b32_e32 v104, v106
	v_add_f32_e32 v104, v104, v106
	ds_swizzle_b32 v106, v105 offset:swizzle(SWAP,1)
	v_mul_f32_e32 v104, 0x3a800000, v104
	s_waitcnt lgkmcnt(0)
	v_add_f32_e32 v105, v105, v106
	ds_swizzle_b32 v106, v105 offset:swizzle(SWAP,2)
	s_waitcnt lgkmcnt(0)
	v_add_f32_e32 v105, v105, v106
	ds_swizzle_b32 v106, v105 offset:swizzle(SWAP,4)
	s_waitcnt lgkmcnt(0)
	v_add_f32_e32 v105, v105, v106
	ds_swizzle_b32 v106, v105 offset:swizzle(SWAP,8)
	s_waitcnt lgkmcnt(0)
	v_add_f32_e32 v105, v105, v106
	ds_swizzle_b32 v106, v105 offset:swizzle(SWAP,16)
	s_waitcnt lgkmcnt(0)
	v_add_f32_e32 v105, v105, v106
	v_mov_b32_e32 v106, v105
	s_nop 1
	v_permlane32_swap_b32_e32 v105, v106
	v_add_f32_e32 v105, v105, v106
	v_pk_add_f32 v[106:107], v[96:97], v[0:1] op_sel_hi:[1,0] neg_lo:[0,1] neg_hi:[0,1]
	v_pk_add_f32 v[96:97], v[90:91], v[0:1] op_sel_hi:[1,0] neg_lo:[0,1] neg_hi:[0,1]
	v_mov_b32_e32 v90, v108
	v_mov_b32_e32 v93, v97
	v_mov_b32_e32 v91, v96
	v_pk_mul_f32 v[92:93], v[92:93], v[92:93]
	v_mul_f32_e32 v110, 0x3a800000, v105
	v_pk_fma_f32 v[90:91], v[90:91], v[90:91], v[92:93]
	v_mov_b32_e32 v92, v106
	v_mov_b32_e32 v93, v94
	v_pk_fma_f32 v[90:91], v[92:93], v[92:93], v[90:91]
	v_mov_b32_e32 v92, v107
	v_mov_b32_e32 v93, v95
	v_pk_fma_f32 v[112:113], v[92:93], v[92:93], v[90:91]
	v_pk_add_f32 v[92:93], v[86:87], v[0:1] op_sel_hi:[1,0] neg_lo:[0,1] neg_hi:[0,1]
	v_pk_add_f32 v[90:91], v[88:89], v[0:1] op_sel_hi:[1,0] neg_lo:[0,1] neg_hi:[0,1]
	v_pk_add_f32 v[88:89], v[82:83], v[0:1] op_sel_hi:[1,0] neg_lo:[0,1] neg_hi:[0,1]
	v_pk_add_f32 v[86:87], v[84:85], v[0:1] op_sel_hi:[1,0] neg_lo:[0,1] neg_hi:[0,1]
	v_mov_b32_e32 v84, v89
	v_mov_b32_e32 v85, v93
	v_mov_b32_e32 v82, v88
	v_mov_b32_e32 v83, v92
	v_pk_mul_f32 v[84:85], v[84:85], v[84:85]
	s_nop 0
	v_pk_fma_f32 v[82:83], v[82:83], v[82:83], v[84:85]
	v_mov_b32_e32 v84, v86
	v_mov_b32_e32 v85, v90
	v_pk_fma_f32 v[82:83], v[84:85], v[84:85], v[82:83]
	v_mov_b32_e32 v84, v87
	v_mov_b32_e32 v85, v91
	v_pk_fma_f32 v[82:83], v[84:85], v[84:85], v[82:83]
	v_add_f32_e32 v84, v112, v113
	v_add_f32_e32 v83, v83, v84
	v_add_f32_e32 v105, v82, v83
	v_pk_add_f32 v[84:85], v[78:79], v[102:103] op_sel_hi:[1,0] neg_lo:[0,1] neg_hi:[0,1]
	v_pk_add_f32 v[82:83], v[80:81], v[102:103] op_sel_hi:[1,0] neg_lo:[0,1] neg_hi:[0,1]
	v_pk_add_f32 v[80:81], v[74:75], v[102:103] op_sel_hi:[1,0] neg_lo:[0,1] neg_hi:[0,1]
	v_pk_add_f32 v[78:79], v[76:77], v[102:103] op_sel_hi:[1,0] neg_lo:[0,1] neg_hi:[0,1]
	v_mov_b32_e32 v76, v85
	v_mov_b32_e32 v77, v81
	v_mov_b32_e32 v74, v84
	v_mov_b32_e32 v75, v80
	v_pk_mul_f32 v[76:77], v[76:77], v[76:77]
	s_nop 0
	v_pk_fma_f32 v[74:75], v[74:75], v[74:75], v[76:77]
	v_mov_b32_e32 v76, v82
	v_mov_b32_e32 v77, v78
	v_pk_fma_f32 v[74:75], v[76:77], v[76:77], v[74:75]
	v_mov_b32_e32 v76, v83
	v_mov_b32_e32 v77, v79
	v_pk_fma_f32 v[112:113], v[76:77], v[76:77], v[74:75]
	v_pk_add_f32 v[76:77], v[70:71], v[102:103] op_sel_hi:[1,0] neg_lo:[0,1] neg_hi:[0,1]
	v_pk_add_f32 v[74:75], v[72:73], v[102:103] op_sel_hi:[1,0] neg_lo:[0,1] neg_hi:[0,1]
	v_pk_add_f32 v[72:73], v[66:67], v[102:103] op_sel_hi:[1,0] neg_lo:[0,1] neg_hi:[0,1]
	v_pk_add_f32 v[70:71], v[68:69], v[102:103] op_sel_hi:[1,0] neg_lo:[0,1] neg_hi:[0,1]
	v_mov_b32_e32 v68, v73
	v_mov_b32_e32 v69, v77
	v_mov_b32_e32 v66, v72
	v_mov_b32_e32 v67, v76
	v_pk_mul_f32 v[68:69], v[68:69], v[68:69]
	s_nop 0
	v_pk_fma_f32 v[66:67], v[66:67], v[66:67], v[68:69]
	v_mov_b32_e32 v68, v70
	v_mov_b32_e32 v69, v74
	v_pk_fma_f32 v[66:67], v[68:69], v[68:69], v[66:67]
	v_mov_b32_e32 v68, v71
	v_mov_b32_e32 v69, v75
	v_pk_fma_f32 v[66:67], v[68:69], v[68:69], v[66:67]
	v_add_f32_e32 v68, v112, v113
	v_add_f32_e32 v67, v67, v68
	v_add_f32_e32 v111, v66, v67
	v_pk_add_f32 v[68:69], v[62:63], v[104:105] op_sel_hi:[1,0] neg_lo:[0,1] neg_hi:[0,1]
	v_pk_add_f32 v[66:67], v[64:65], v[104:105] op_sel_hi:[1,0] neg_lo:[0,1] neg_hi:[0,1]
	v_pk_add_f32 v[64:65], v[58:59], v[104:105] op_sel_hi:[1,0] neg_lo:[0,1] neg_hi:[0,1]
	v_pk_add_f32 v[62:63], v[60:61], v[104:105] op_sel_hi:[1,0] neg_lo:[0,1] neg_hi:[0,1]
	v_mov_b32_e32 v60, v69
	v_mov_b32_e32 v61, v65
	v_mov_b32_e32 v58, v68
	v_mov_b32_e32 v59, v64
	v_pk_mul_f32 v[60:61], v[60:61], v[60:61]
	s_nop 0
	v_pk_fma_f32 v[58:59], v[58:59], v[58:59], v[60:61]
	v_mov_b32_e32 v60, v66
	v_mov_b32_e32 v61, v62
	v_pk_fma_f32 v[58:59], v[60:61], v[60:61], v[58:59]
	v_mov_b32_e32 v60, v67
	v_mov_b32_e32 v61, v63
	v_pk_fma_f32 v[112:113], v[60:61], v[60:61], v[58:59]
	v_pk_add_f32 v[60:61], v[54:55], v[104:105] op_sel_hi:[1,0] neg_lo:[0,1] neg_hi:[0,1]
	v_pk_add_f32 v[58:59], v[56:57], v[104:105] op_sel_hi:[1,0] neg_lo:[0,1] neg_hi:[0,1]
	v_pk_add_f32 v[56:57], v[50:51], v[104:105] op_sel_hi:[1,0] neg_lo:[0,1] neg_hi:[0,1]
	v_pk_add_f32 v[54:55], v[52:53], v[104:105] op_sel_hi:[1,0] neg_lo:[0,1] neg_hi:[0,1]
	v_mov_b32_e32 v52, v57
	v_mov_b32_e32 v53, v61
	v_mov_b32_e32 v50, v56
	v_mov_b32_e32 v51, v60
	v_pk_mul_f32 v[52:53], v[52:53], v[52:53]
	s_nop 0
	v_pk_fma_f32 v[50:51], v[50:51], v[50:51], v[52:53]
	v_mov_b32_e32 v52, v54
	v_mov_b32_e32 v53, v58
	v_pk_fma_f32 v[50:51], v[52:53], v[52:53], v[50:51]
	v_mov_b32_e32 v52, v55
	v_mov_b32_e32 v53, v59
	v_pk_fma_f32 v[50:51], v[52:53], v[52:53], v[50:51]
	v_add_f32_e32 v52, v112, v113
	v_add_f32_e32 v51, v51, v52
	v_add_f32_e32 v114, v50, v51
	v_pk_add_f32 v[52:53], v[46:47], v[110:111] op_sel_hi:[1,0] neg_lo:[0,1] neg_hi:[0,1]
	v_pk_add_f32 v[50:51], v[48:49], v[110:111] op_sel_hi:[1,0] neg_lo:[0,1] neg_hi:[0,1]
	v_pk_add_f32 v[48:49], v[42:43], v[110:111] op_sel_hi:[1,0] neg_lo:[0,1] neg_hi:[0,1]
	v_pk_add_f32 v[46:47], v[44:45], v[110:111] op_sel_hi:[1,0] neg_lo:[0,1] neg_hi:[0,1]
	v_mov_b32_e32 v44, v53
	v_mov_b32_e32 v45, v49
	v_mov_b32_e32 v42, v52
	v_mov_b32_e32 v43, v48
	v_pk_mul_f32 v[44:45], v[44:45], v[44:45]
	s_nop 0
	v_pk_fma_f32 v[42:43], v[42:43], v[42:43], v[44:45]
	v_mov_b32_e32 v44, v50
	v_mov_b32_e32 v45, v46
	v_pk_fma_f32 v[42:43], v[44:45], v[44:45], v[42:43]
	v_mov_b32_e32 v44, v51
	v_mov_b32_e32 v45, v47
	v_pk_fma_f32 v[112:113], v[44:45], v[44:45], v[42:43]
	v_pk_add_f32 v[44:45], v[38:39], v[110:111] op_sel_hi:[1,0] neg_lo:[0,1] neg_hi:[0,1]
	v_pk_add_f32 v[42:43], v[40:41], v[110:111] op_sel_hi:[1,0] neg_lo:[0,1] neg_hi:[0,1]
	v_pk_add_f32 v[40:41], v[34:35], v[110:111] op_sel_hi:[1,0] neg_lo:[0,1] neg_hi:[0,1]
	v_pk_add_f32 v[38:39], v[36:37], v[110:111] op_sel_hi:[1,0] neg_lo:[0,1] neg_hi:[0,1]
	v_mov_b32_e32 v36, v41
	v_mov_b32_e32 v37, v45
	v_mov_b32_e32 v34, v40
	v_mov_b32_e32 v35, v44
	v_pk_mul_f32 v[36:37], v[36:37], v[36:37]
	s_nop 0
	v_pk_fma_f32 v[34:35], v[34:35], v[34:35], v[36:37]
	v_mov_b32_e32 v36, v38
	v_mov_b32_e32 v37, v42
	v_pk_fma_f32 v[34:35], v[36:37], v[36:37], v[34:35]
	v_mov_b32_e32 v36, v39
	v_mov_b32_e32 v37, v43
	v_pk_fma_f32 v[34:35], v[36:37], v[36:37], v[34:35]
	v_add_f32_e32 v36, v112, v113
	v_add_f32_e32 v35, v35, v36
	v_add_f32_e32 v113, v34, v35
	ds_swizzle_b32 v34, v105 offset:swizzle(SWAP,1)
	s_waitcnt lgkmcnt(0)
	v_add_f32_e32 v34, v105, v34
	ds_swizzle_b32 v35, v34 offset:swizzle(SWAP,2)
	s_waitcnt lgkmcnt(0)
	v_add_f32_e32 v34, v34, v35
	ds_swizzle_b32 v35, v34 offset:swizzle(SWAP,4)
	s_waitcnt lgkmcnt(0)
	v_add_f32_e32 v34, v34, v35
	ds_swizzle_b32 v35, v34 offset:swizzle(SWAP,8)
	s_waitcnt lgkmcnt(0)
	v_add_f32_e32 v34, v34, v35
	ds_swizzle_b32 v35, v34 offset:swizzle(SWAP,16)
	s_waitcnt lgkmcnt(0)
	v_add_f32_e32 v35, v34, v35
	ds_swizzle_b32 v34, v111 offset:swizzle(SWAP,1)
	v_mov_b32_e32 v37, v35
	s_waitcnt lgkmcnt(0)
	v_add_f32_e32 v34, v111, v34
	ds_swizzle_b32 v36, v34 offset:swizzle(SWAP,2)
	v_permlane32_swap_b32_e32 v35, v37
	s_waitcnt lgkmcnt(0)
	v_add_f32_e32 v34, v34, v36
	ds_swizzle_b32 v36, v34 offset:swizzle(SWAP,4)
	s_waitcnt lgkmcnt(0)
	v_add_f32_e32 v34, v34, v36
	ds_swizzle_b32 v36, v34 offset:swizzle(SWAP,8)
	s_waitcnt lgkmcnt(0)
	v_add_f32_e32 v34, v34, v36
	ds_swizzle_b32 v36, v34 offset:swizzle(SWAP,16)
	s_waitcnt lgkmcnt(0)
	v_add_f32_e32 v34, v34, v36
	v_mov_b32_e32 v36, v34
	s_nop 1
	v_permlane32_swap_b32_e32 v34, v36
	v_pk_add_f32 v[36:37], v[34:35], v[36:37]
	v_mov_b64_e32 v[34:35], s[10:11]
	s_mov_b32 s10, 0x3a800000
	v_pk_fma_f32 v[36:37], v[36:37], s[10:11], v[34:35] op_sel_hi:[1,0,0]
	s_nop 0
	v_mul_f32_e32 v105, 0x4b800000, v37
	v_cmp_gt_f32_e64 s[48:49], s5, v37
	v_cmp_gt_f32_e32 vcc, s5, v36
	s_nop 0
	v_cndmask_b32_e64 v37, v37, v105, s[48:49]
	v_rsq_f32_e32 v37, v37
	s_nop 0
	v_mul_f32_e32 v105, 0x45800000, v37
	v_cndmask_b32_e64 v116, v37, v105, s[48:49]
	v_mul_f32_e32 v37, 0x4b800000, v36
	v_cndmask_b32_e32 v36, v36, v37, vcc
	v_rsq_f32_e32 v36, v36
	s_nop 0
	v_mul_f32_e32 v37, 0x45800000, v36
	v_cndmask_b32_e32 v112, v36, v37, vcc
	ds_swizzle_b32 v36, v114 offset:swizzle(SWAP,1)
	s_waitcnt lgkmcnt(0)
	v_add_f32_e32 v36, v114, v36
	ds_swizzle_b32 v37, v36 offset:swizzle(SWAP,2)
	s_waitcnt lgkmcnt(0)
	v_add_f32_e32 v36, v36, v37
	ds_swizzle_b32 v37, v36 offset:swizzle(SWAP,4)
	s_waitcnt lgkmcnt(0)
	v_add_f32_e32 v36, v36, v37
	ds_swizzle_b32 v37, v36 offset:swizzle(SWAP,8)
	s_waitcnt lgkmcnt(0)
	v_add_f32_e32 v36, v36, v37
	ds_swizzle_b32 v37, v36 offset:swizzle(SWAP,16)
	s_waitcnt lgkmcnt(0)
	v_add_f32_e32 v37, v36, v37
	ds_swizzle_b32 v36, v113 offset:swizzle(SWAP,1)
	v_mov_b32_e32 v115, v37
	s_waitcnt lgkmcnt(0)
	v_add_f32_e32 v36, v113, v36
	ds_swizzle_b32 v105, v36 offset:swizzle(SWAP,2)
	v_permlane32_swap_b32_e32 v37, v115
	s_waitcnt lgkmcnt(0)
	v_add_f32_e32 v36, v36, v105
	ds_swizzle_b32 v105, v36 offset:swizzle(SWAP,4)
	s_waitcnt lgkmcnt(0)
	v_add_f32_e32 v36, v36, v105
	ds_swizzle_b32 v105, v36 offset:swizzle(SWAP,8)
	s_waitcnt lgkmcnt(0)
	v_add_f32_e32 v36, v36, v105
	ds_swizzle_b32 v105, v36 offset:swizzle(SWAP,16)
	s_waitcnt lgkmcnt(0)
	v_add_f32_e32 v36, v36, v105
	v_mov_b32_e32 v114, v36
	s_nop 1
	v_permlane32_swap_b32_e32 v36, v114
	v_pk_add_f32 v[36:37], v[36:37], v[114:115]
	s_nop 0
	v_pk_fma_f32 v[34:35], v[36:37], s[10:11], v[34:35] op_sel_hi:[1,0,0]
	s_nop 0
	v_mul_f32_e32 v36, 0x4b800000, v35
	v_cmp_gt_f32_e64 s[48:49], s5, v35
	v_cmp_gt_f32_e32 vcc, s5, v34
	s_nop 0
	v_cndmask_b32_e64 v35, v35, v36, s[48:49]
	v_rsq_f32_e32 v35, v35
	s_nop 0
	v_mul_f32_e32 v36, 0x45800000, v35
	v_cndmask_b32_e64 v118, v35, v36, s[48:49]
	v_mul_f32_e32 v35, 0x4b800000, v34
	v_cndmask_b32_e32 v34, v34, v35, vcc
	v_rsq_f32_e32 v34, v34
	s_nop 0
	v_mul_f32_e32 v35, 0x45800000, v34
	v_cndmask_b32_e32 v114, v34, v35, vcc
	s_and_saveexec_b64 s[48:49], s[40:41]
	s_cbranch_execz .LBB0_727
	v_cndmask_b32_e64 v34, v110, v104, s[46:47]
	v_cndmask_b32_e64 v34, v34, v102, s[44:45]
	v_cndmask_b32_e64 v34, v34, v0, s[42:43]
	v_cndmask_b32_e64 v0, v114, v118, s[46:47]
	v_add_u32_e32 v36, s4, v103
	v_cndmask_b32_e64 v0, v0, v112, s[44:45]
	v_ashrrev_i32_e32 v37, 31, v36
	v_cndmask_b32_e64 v35, v0, v116, s[42:43]
	v_lshl_add_u64 v[36:37], v[36:37], 3, s[8:9]
	global_store_dwordx2 v[36:37], v[34:35], off
